# attention loops: K-fragment LDS reads of the first QK step issued right after the iteration barrier, ahead of the next-tile load bookkeeping
# baseline (speedup 1.0000x reference)
.LBB0_717:
	s_add_i32 s25, s60, 1
	s_and_b32 s24, s25, 3
	s_mul_i32 s23, s24, 0x3400
	v_add_u32_e32 v80, s23, v227
	ds_read_b128 v[164:167], v80
	ds_read_b128 v[168:171], v80 offset:32
	ds_read_b128 v[172:175], v80 offset:6656
	ds_read_b128 v[176:179], v80 offset:6688
	ds_read_b128 v[180:183], v80 offset:64
	ds_read_b128 v[184:187], v80 offset:96
	ds_read_b128 v[188:191], v80 offset:6720
	ds_read_b128 v[192:195], v80 offset:6752
	ds_read_b128 v[236:239], v80 offset:128
	ds_read_b128 v[240:243], v80 offset:160
	ds_read_b128 v[244:247], v80 offset:6784
	ds_read_b128 v[160:163], v80 offset:6816
	s_add_i32 s22, s60, 3
	s_cmp_lt_u32 s22, s15
	s_cselect_b64 s[8:9], -1, 0
	s_cmp_ge_u32 s22, s15
	s_cbranch_scc1 .LBB0_721
	v_lshl_add_u64 v[50:51], v[206:207], 0, v[220:221]
	global_load_dwordx4 v[140:143], v[50:51], off
	s_and_saveexec_b64 s[12:13], s[42:43]
	s_cbranch_execz .LBB0_720
	v_lshl_add_u64 v[50:51], v[208:209], 0, v[218:219]
	global_load_dwordx4 v[136:139], v[50:51], off

.Lpsq_1:
	s_waitcnt lgkmcnt(11)
	v_mfma_f32_32x32x16_bf16 v[80:95], v[164:167], v[112:115], v[32:47]
	v_exp_f32_e32 v64, v64
	v_exp_f32_e32 v66, v66
	v_exp_f32_e32 v68, v68
	v_exp_f32_e32 v164, v96
	v_exp_f32_e32 v65, v65
	v_exp_f32_e32 v165, v97
	v_exp_f32_e32 v70, v70
	v_add_f32_e32 v96, v66, v64
	v_exp_f32_e32 v67, v67
	v_add_f32_e32 v96, v68, v96
	v_add_f32_e32 v96, v70, v96
	s_waitcnt lgkmcnt(10)
	v_mfma_f32_32x32x16_bf16 v[80:95], v[168:171], v[116:119], v[80:95]
	v_exp_f32_e32 v169, v99
	v_exp_f32_e32 v168, v98
	v_add_f32_e32 v98, v67, v65
	v_exp_f32_e32 v166, v100
	v_add_f32_e32 v99, v169, v165
	v_exp_f32_e32 v69, v69
	v_exp_f32_e32 v167, v101
	v_exp_f32_e32 v170, v102
	v_add_f32_e32 v97, v168, v164
	v_add_f32_e32 v97, v166, v97
	v_add_f32_e32 v98, v69, v98
	v_add_f32_e32 v99, v167, v99
	v_add_f32_e32 v97, v170, v97
	s_waitcnt lgkmcnt(7)
	v_mfma_f32_32x32x16_bf16 v[80:95], v[180:183], v[120:123], v[80:95]
	v_exp_f32_e32 v71, v71
	v_exp_f32_e32 v171, v103
	v_exp_f32_e32 v180, v72
	v_exp_f32_e32 v181, v104
	v_exp_f32_e32 v182, v73
	v_exp_f32_e32 v183, v105
	v_add_f32_e32 v98, v71, v98
	v_add_f32_e32 v99, v171, v99
	v_add_f32_e32 v72, v180, v96
	v_add_f32_e32 v73, v181, v97
	v_add_f32_e32 v96, v182, v98
	v_add_f32_e32 v97, v183, v99
	v_exp_f32_e32 v235, v76
	v_cvt_pk_bf16_f32 v76, v180, v182
	s_waitcnt lgkmcnt(6)
	v_mfma_f32_32x32x16_bf16 v[80:95], v[184:187], v[124:127], v[80:95]
	v_exp_f32_e32 v184, v74
	v_exp_f32_e32 v185, v106
	v_exp_f32_e32 v186, v75
	v_exp_f32_e32 v187, v107
	v_add_f32_e32 v72, v184, v72
	v_add_f32_e32 v73, v185, v73
	v_add_f32_e32 v74, v186, v96
	v_add_f32_e32 v75, v187, v97
	v_add_f32_e32 v72, v235, v72
	s_waitcnt lgkmcnt(3)
	v_mfma_f32_32x32x16_bf16 v[80:95], v[236:239], v[128:131], v[80:95]
	v_exp_f32_e32 v237, v77
	v_exp_f32_e32 v236, v108
	v_exp_f32_e32 v238, v109
	v_exp_f32_e32 v239, v78
	v_exp_f32_e32 v79, v79
	v_add_f32_e32 v74, v237, v74
	v_add_f32_e32 v73, v236, v73
	v_add_f32_e32 v75, v238, v75
	v_add_f32_e32 v72, v239, v72
	v_add_f32_e32 v74, v79, v74
	v_cvt_pk_bf16_f32 v77, v184, v186
	v_cvt_pk_bf16_f32 v78, v235, v237
	s_waitcnt lgkmcnt(2)
	v_mfma_f32_32x32x16_bf16 v[80:95], v[240:243], v[132:135], v[80:95]
	v_exp_f32_e32 v240, v110
	v_exp_f32_e32 v241, v111
	v_cvt_pk_bf16_f32 v79, v239, v79
	v_add_f32_e32 v73, v240, v73
	v_add_f32_e32 v75, v241, v75
	v_add_f32_e32 v72, v73, v72
	v_add_f32_e32 v73, v75, v74
	v_cvt_pk_bf16_f32 v74, v68, v69
	v_cvt_pk_bf16_f32 v75, v70, v71
	v_mfma_f32_32x32x16_bf16 v[96:111], v[172:175], v[112:115], v[32:47]
	v_add_f32_e32 v172, v73, v72
	v_cvt_pk_bf16_f32 v72, v64, v65
	v_cvt_pk_bf16_f32 v73, v66, v67
	v_cvt_pk_bf16_f32 v64, v164, v165
	v_cvt_pk_bf16_f32 v65, v168, v169
	v_cvt_pk_bf16_f32 v66, v166, v167
	v_cvt_pk_bf16_f32 v67, v170, v171
	v_mfma_f32_32x32x16_bf16 v[96:111], v[176:179], v[116:119], v[96:111]
	v_cvt_pk_bf16_f32 v68, v181, v183
	v_cvt_pk_bf16_f32 v69, v185, v187
	v_cvt_pk_bf16_f32 v70, v236, v238
	v_cvt_pk_bf16_f32 v71, v240, v241
	v_add_f32_e32 v234, v234, v172
	v_mfma_f32_32x32x16_bf16 v[96:111], v[188:191], v[120:123], v[96:111]
	v_mfma_f32_32x32x16_bf16 v[96:111], v[192:195], v[124:127], v[96:111]
	s_waitcnt lgkmcnt(1)
	v_mfma_f32_32x32x16_bf16 v[96:111], v[244:247], v[128:131], v[96:111]
	s_and_b32 s23, s60, 2
	s_waitcnt lgkmcnt(0)
	v_mfma_f32_32x32x16_bf16 v[96:111], v[160:163], v[132:135], v[96:111]
	s_mul_i32 s26, s23, 0x3000
	v_add_u32_e32 v164, s26, v232
	ds_read_b64_tr_b16 v[192:193], v164 offset:53248
	ds_read_b64_tr_b16 v[194:195], v164 offset:54784
	ds_read_b64_tr_b16 v[190:191], v164 offset:54848
	ds_read_b64_tr_b16 v[188:189], v164 offset:53312
	ds_read_b64_tr_b16 v[184:185], v164 offset:56320
	ds_read_b64_tr_b16 v[186:187], v164 offset:57856
	ds_read_b64_tr_b16 v[182:183], v164 offset:57920
	ds_read_b64_tr_b16 v[180:181], v164 offset:56384
	ds_read_b64_tr_b16 v[176:177], v164 offset:59392
	ds_read_b64_tr_b16 v[178:179], v164 offset:60928
	ds_read_b64_tr_b16 v[174:175], v164 offset:60992
	ds_read_b64_tr_b16 v[172:173], v164 offset:59456
	ds_read_b64_tr_b16 v[168:169], v164 offset:62464
	ds_read_b64_tr_b16 v[170:171], v164 offset:64000
	ds_read_b64_tr_b16 v[166:167], v164 offset:64064
	ds_read_b64_tr_b16 v[164:165], v164 offset:62528
	s_cmp_lt_u32 s25, s7
	s_cbranch_scc1 .LBB0_732
	v_add_u32_e32 v160, 32, v233
	v_cmp_le_i32_e32 vcc, v160, v229
	v_add_u32_e32 v160, 33, v233
	s_nop 0
	v_cndmask_b32_e32 v96, v224, v96, vcc
	v_cmp_lt_i32_e32 vcc, v233, v229
	s_nop 1
	v_cndmask_b32_e32 v81, v224, v81, vcc
	v_cmp_le_i32_e32 vcc, v233, v229
	s_nop 1
	v_cndmask_b32_e32 v80, v224, v80, vcc
	v_cmp_le_i32_e32 vcc, v160, v229
	v_add_u32_e32 v160, 2, v233
	s_nop 0
	v_cndmask_b32_e32 v97, v224, v97, vcc
	v_cmp_le_i32_e32 vcc, v160, v229
	v_add_u32_e32 v160, 34, v233
	s_nop 0
	v_cndmask_b32_e32 v82, v224, v82, vcc
	v_cmp_le_i32_e32 vcc, v160, v229
	v_add_u32_e32 v160, 3, v233
	s_nop 0
	v_cndmask_b32_e32 v98, v224, v98, vcc
	v_cmp_le_i32_e32 vcc, v160, v229
	v_add_u32_e32 v160, 35, v233
	s_nop 0
	v_cndmask_b32_e32 v83, v224, v83, vcc
	v_cmp_le_i32_e32 vcc, v160, v229
	v_add_u32_e32 v160, 8, v233
	s_nop 0
	v_cndmask_b32_e32 v99, v224, v99, vcc
	v_cmp_le_i32_e32 vcc, v160, v229
	v_add_u32_e32 v160, 40, v233
	s_nop 0
	v_cndmask_b32_e32 v84, v224, v84, vcc
	v_cmp_le_i32_e32 vcc, v160, v229
	v_add_u32_e32 v160, 9, v233
	s_nop 0
	v_cndmask_b32_e32 v100, v224, v100, vcc
	v_cmp_le_i32_e32 vcc, v160, v229
	v_add_u32_e32 v160, 41, v233
	s_nop 0
	v_cndmask_b32_e32 v85, v224, v85, vcc
	v_cmp_le_i32_e32 vcc, v160, v229
	v_add_u32_e32 v160, 10, v233
	s_nop 0
	v_cndmask_b32_e32 v101, v224, v101, vcc
	v_cmp_le_i32_e32 vcc, v160, v229
	v_add_u32_e32 v160, 42, v233
	s_nop 0
	v_cndmask_b32_e32 v86, v224, v86, vcc
	v_cmp_le_i32_e32 vcc, v160, v229
	v_add_u32_e32 v160, 11, v233
	s_nop 0
	v_cndmask_b32_e32 v102, v224, v102, vcc
	v_cmp_le_i32_e32 vcc, v160, v229
	v_add_u32_e32 v160, 43, v233
	s_nop 0
	v_cndmask_b32_e32 v87, v224, v87, vcc
	v_cmp_le_i32_e32 vcc, v160, v229
	v_add_u32_e32 v160, 16, v233
	s_nop 0
	v_cndmask_b32_e32 v103, v224, v103, vcc
	v_cmp_le_i32_e32 vcc, v160, v229
	v_add_u32_e32 v160, 48, v233
	s_nop 0
	v_cndmask_b32_e32 v88, v224, v88, vcc
	v_cmp_le_i32_e32 vcc, v160, v229
	v_add_u32_e32 v160, 17, v233
	s_nop 0
	v_cndmask_b32_e32 v104, v224, v104, vcc
	v_cmp_le_i32_e32 vcc, v160, v229
	v_add_u32_e32 v160, 49, v233
	s_nop 0
	v_cndmask_b32_e32 v89, v224, v89, vcc
	v_cmp_le_i32_e32 vcc, v160, v229
	v_add_u32_e32 v160, 18, v233
	s_nop 0
	v_cndmask_b32_e32 v105, v224, v105, vcc
	v_cmp_le_i32_e32 vcc, v160, v229
	v_add_u32_e32 v160, 50, v233
	s_nop 0
	v_cndmask_b32_e32 v90, v224, v90, vcc
	v_cmp_le_i32_e32 vcc, v160, v229
	v_add_u32_e32 v160, 19, v233
	s_nop 0
	v_cndmask_b32_e32 v106, v224, v106, vcc
	v_cmp_le_i32_e32 vcc, v160, v229
	v_add_u32_e32 v160, 51, v233
	s_nop 0
	v_cndmask_b32_e32 v91, v224, v91, vcc
	v_cmp_le_i32_e32 vcc, v160, v229
	v_add_u32_e32 v160, 24, v233
	s_nop 0
	v_cndmask_b32_e32 v107, v224, v107, vcc
	v_cmp_le_i32_e32 vcc, v160, v229
	v_add_u32_e32 v160, 56, v233
	s_nop 0
	v_cndmask_b32_e32 v92, v224, v92, vcc
	v_cmp_le_i32_e32 vcc, v160, v229
	v_add_u32_e32 v160, 25, v233
	s_nop 0
	v_cndmask_b32_e32 v108, v224, v108, vcc
	v_cmp_le_i32_e32 vcc, v160, v229
	v_add_u32_e32 v160, 57, v233
	s_nop 0
	v_cndmask_b32_e32 v93, v224, v93, vcc
	v_cmp_le_i32_e32 vcc, v160, v229
	v_add_u32_e32 v160, 26, v233
	s_nop 0
	v_cndmask_b32_e32 v109, v224, v109, vcc
	v_cmp_le_i32_e32 vcc, v160, v229
	v_add_u32_e32 v160, 58, v233
	s_nop 0
	v_cndmask_b32_e32 v94, v224, v94, vcc
	v_cmp_le_i32_e32 vcc, v160, v229
	v_add_u32_e32 v160, 27, v233
	s_nop 0
	v_cndmask_b32_e32 v110, v224, v110, vcc
	v_cmp_le_i32_e32 vcc, v160, v229
	v_add_u32_e32 v160, 59, v233
	s_nop 0
	v_cndmask_b32_e32 v95, v224, v95, vcc
	v_cmp_le_i32_e32 vcc, v160, v229
	s_nop 1
	v_cndmask_b32_e32 v111, v224, v111, vcc

.LBB0_764:
	s_add_i32 s22, s15, 1
	s_and_b32 s17, s22, 3
	s_mul_i32 s23, s17, 0x3400
	v_add_u32_e32 v80, s23, v228
	ds_read_b128 v[164:167], v80
	ds_read_b128 v[168:171], v80 offset:32
	ds_read_b128 v[172:175], v80 offset:6656
	ds_read_b128 v[176:179], v80 offset:6688
	ds_read_b128 v[180:183], v80 offset:64
	ds_read_b128 v[184:187], v80 offset:96
	ds_read_b128 v[188:191], v80 offset:6720
	ds_read_b128 v[192:195], v80 offset:6752
	ds_read_b128 v[234:237], v80 offset:128
	ds_read_b128 v[238:241], v80 offset:160
	ds_read_b128 v[242:245], v80 offset:6784
	ds_read_b128 v[160:163], v80 offset:6816
	s_add_i32 s14, s15, 3
	s_cmp_lt_i32 s14, s7
	s_cselect_b64 s[8:9], -1, 0
	s_cmp_ge_i32 s14, s7
	s_cbranch_scc1 .LBB0_768
	v_lshl_add_u64 v[50:51], v[206:207], 0, v[220:221]
	global_load_dwordx4 v[140:143], v[50:51], off
	s_and_saveexec_b64 s[12:13], s[42:43]
	s_cbranch_execz .LBB0_767
	v_lshl_add_u64 v[50:51], v[208:209], 0, v[218:219]
	global_load_dwordx4 v[136:139], v[50:51], off

.Lpsq_3:
	s_waitcnt lgkmcnt(11)
	v_mfma_f32_32x32x16_bf16 v[80:95], v[164:167], v[112:115], v[32:47]
	v_exp_f32_e32 v64, v64
	v_exp_f32_e32 v66, v66
	v_exp_f32_e32 v68, v68
	v_exp_f32_e32 v164, v96
	v_exp_f32_e32 v65, v65
	v_exp_f32_e32 v165, v97
	v_exp_f32_e32 v70, v70
	v_add_f32_e32 v96, v66, v64
	v_exp_f32_e32 v67, v67
	v_add_f32_e32 v96, v68, v96
	v_add_f32_e32 v96, v70, v96
	s_waitcnt lgkmcnt(10)
	v_mfma_f32_32x32x16_bf16 v[80:95], v[168:171], v[116:119], v[80:95]
	v_exp_f32_e32 v169, v99
	v_exp_f32_e32 v168, v98
	v_add_f32_e32 v98, v67, v65
	v_exp_f32_e32 v166, v100
	v_add_f32_e32 v99, v169, v165
	v_exp_f32_e32 v69, v69
	v_exp_f32_e32 v167, v101
	v_exp_f32_e32 v170, v102
	v_add_f32_e32 v97, v168, v164
	v_add_f32_e32 v97, v166, v97
	v_add_f32_e32 v98, v69, v98
	v_add_f32_e32 v99, v167, v99
	v_add_f32_e32 v97, v170, v97
	s_waitcnt lgkmcnt(7)
	v_mfma_f32_32x32x16_bf16 v[80:95], v[180:183], v[120:123], v[80:95]
	v_exp_f32_e32 v71, v71
	v_exp_f32_e32 v171, v103
	v_exp_f32_e32 v180, v72
	v_exp_f32_e32 v181, v104
	v_exp_f32_e32 v182, v73
	v_exp_f32_e32 v183, v105
	v_add_f32_e32 v98, v71, v98
	v_add_f32_e32 v99, v171, v99
	v_add_f32_e32 v72, v180, v96
	v_add_f32_e32 v73, v181, v97
	v_add_f32_e32 v96, v182, v98
	v_add_f32_e32 v97, v183, v99
	s_waitcnt lgkmcnt(6)
	v_mfma_f32_32x32x16_bf16 v[80:95], v[184:187], v[124:127], v[80:95]
	v_exp_f32_e32 v184, v74
	v_exp_f32_e32 v185, v106
	v_exp_f32_e32 v186, v75
	v_exp_f32_e32 v187, v107
	v_add_f32_e32 v72, v184, v72
	v_add_f32_e32 v73, v185, v73
	v_add_f32_e32 v74, v186, v96
	v_add_f32_e32 v75, v187, v97
	s_waitcnt lgkmcnt(3)
	v_mfma_f32_32x32x16_bf16 v[80:95], v[234:237], v[128:131], v[80:95]
	v_exp_f32_e32 v236, v77
	v_exp_f32_e32 v234, v76
	v_exp_f32_e32 v235, v108
	v_exp_f32_e32 v237, v109
	v_exp_f32_e32 v79, v79
	v_add_f32_e32 v74, v236, v74
	v_add_f32_e32 v72, v234, v72
	v_add_f32_e32 v73, v235, v73
	v_add_f32_e32 v75, v237, v75
	v_add_f32_e32 v74, v79, v74
	v_cvt_pk_bf16_f32 v76, v180, v182
	v_cvt_pk_bf16_f32 v77, v184, v186
	s_waitcnt lgkmcnt(2)
	v_mfma_f32_32x32x16_bf16 v[80:95], v[238:241], v[132:135], v[80:95]
	v_exp_f32_e32 v238, v78
	v_exp_f32_e32 v239, v110
	v_exp_f32_e32 v240, v111
	v_add_f32_e32 v72, v238, v72
	v_add_f32_e32 v73, v239, v73
	v_add_f32_e32 v75, v240, v75
	v_add_f32_e32 v72, v73, v72
	v_add_f32_e32 v73, v75, v74
	v_cvt_pk_bf16_f32 v74, v68, v69
	v_cvt_pk_bf16_f32 v75, v70, v71
	v_mfma_f32_32x32x16_bf16 v[96:111], v[172:175], v[112:115], v[32:47]
	v_add_f32_e32 v172, v73, v72
	v_cvt_pk_bf16_f32 v72, v64, v65
	v_cvt_pk_bf16_f32 v73, v66, v67
	v_cvt_pk_bf16_f32 v64, v164, v165
	v_cvt_pk_bf16_f32 v65, v168, v169
	v_cvt_pk_bf16_f32 v66, v166, v167
	v_cvt_pk_bf16_f32 v67, v170, v171
	v_mfma_f32_32x32x16_bf16 v[96:111], v[176:179], v[116:119], v[96:111]
	v_cvt_pk_bf16_f32 v78, v234, v236
	v_cvt_pk_bf16_f32 v79, v238, v79
	v_cvt_pk_bf16_f32 v68, v181, v183
	v_cvt_pk_bf16_f32 v69, v185, v187
	v_cvt_pk_bf16_f32 v70, v235, v237
	v_cvt_pk_bf16_f32 v71, v239, v240
	v_add_f32_e32 v233, v233, v172
	v_mfma_f32_32x32x16_bf16 v[96:111], v[188:191], v[120:123], v[96:111]
	v_mfma_f32_32x32x16_bf16 v[96:111], v[192:195], v[124:127], v[96:111]
	s_waitcnt lgkmcnt(1)
	v_mfma_f32_32x32x16_bf16 v[96:111], v[242:245], v[128:131], v[96:111]
	s_and_b32 s15, s15, 2
	s_waitcnt lgkmcnt(0)
	v_mfma_f32_32x32x16_bf16 v[96:111], v[160:163], v[132:135], v[96:111]
	s_mul_i32 s23, s15, 0x3000
	v_add_u32_e32 v164, s23, v231
	ds_read_b64_tr_b16 v[192:193], v164 offset:53248
	ds_read_b64_tr_b16 v[194:195], v164 offset:54784
	ds_read_b64_tr_b16 v[190:191], v164 offset:54848
	ds_read_b64_tr_b16 v[188:189], v164 offset:53312
	ds_read_b64_tr_b16 v[184:185], v164 offset:56320
	ds_read_b64_tr_b16 v[186:187], v164 offset:57856
	ds_read_b64_tr_b16 v[182:183], v164 offset:57920
	ds_read_b64_tr_b16 v[180:181], v164 offset:56384
	ds_read_b64_tr_b16 v[176:177], v164 offset:59392
	ds_read_b64_tr_b16 v[178:179], v164 offset:60928
	ds_read_b64_tr_b16 v[174:175], v164 offset:60992
	ds_read_b64_tr_b16 v[172:173], v164 offset:59456
	ds_read_b64_tr_b16 v[168:169], v164 offset:62464
	ds_read_b64_tr_b16 v[170:171], v164 offset:64000
	ds_read_b64_tr_b16 v[166:167], v164 offset:64064
	ds_read_b64_tr_b16 v[164:165], v164 offset:62528
	s_cmp_lt_i32 s22, s2
	s_cbranch_scc1 .LBB0_779
	v_subrev_u32_e32 v160, 32, v232
	v_cmp_le_i32_e32 vcc, v232, v229
	s_nop 1
	v_cndmask_b32_e32 v96, v224, v96, vcc
	v_cmp_lt_i32_e32 vcc, v160, v229
	s_nop 1
	v_cndmask_b32_e32 v81, v224, v81, vcc
	v_cmp_le_i32_e32 vcc, v160, v229
	v_add_u32_e32 v160, 1, v232
	s_nop 0
	v_cndmask_b32_e32 v80, v224, v80, vcc
	v_cmp_le_i32_e32 vcc, v160, v229
	v_subrev_u32_e32 v160, 30, v232
	s_nop 0
	v_cndmask_b32_e32 v97, v224, v97, vcc
	v_cmp_le_i32_e32 vcc, v160, v229
	v_add_u32_e32 v160, 2, v232
	s_nop 0
	v_cndmask_b32_e32 v82, v224, v82, vcc
	v_cmp_le_i32_e32 vcc, v160, v229
	v_subrev_u32_e32 v160, 29, v232
	s_nop 0
	v_cndmask_b32_e32 v98, v224, v98, vcc
	v_cmp_le_i32_e32 vcc, v160, v229
	v_add_u32_e32 v160, 3, v232
	s_nop 0
	v_cndmask_b32_e32 v83, v224, v83, vcc
	v_cmp_le_i32_e32 vcc, v160, v229
	v_subrev_u32_e32 v160, 24, v232
	s_nop 0
	v_cndmask_b32_e32 v99, v224, v99, vcc
	v_cmp_le_i32_e32 vcc, v160, v229
	v_add_u32_e32 v160, 8, v232
	s_nop 0
	v_cndmask_b32_e32 v84, v224, v84, vcc
	v_cmp_le_i32_e32 vcc, v160, v229
	v_subrev_u32_e32 v160, 23, v232
	s_nop 0
	v_cndmask_b32_e32 v100, v224, v100, vcc
	v_cmp_le_i32_e32 vcc, v160, v229
	v_add_u32_e32 v160, 9, v232
	s_nop 0
	v_cndmask_b32_e32 v85, v224, v85, vcc
	v_cmp_le_i32_e32 vcc, v160, v229
	v_subrev_u32_e32 v160, 22, v232
	s_nop 0
	v_cndmask_b32_e32 v101, v224, v101, vcc
	v_cmp_le_i32_e32 vcc, v160, v229
	v_add_u32_e32 v160, 10, v232
	s_nop 0
	v_cndmask_b32_e32 v86, v224, v86, vcc
	v_cmp_le_i32_e32 vcc, v160, v229
	v_subrev_u32_e32 v160, 21, v232
	s_nop 0
	v_cndmask_b32_e32 v102, v224, v102, vcc
	v_cmp_le_i32_e32 vcc, v160, v229
	v_add_u32_e32 v160, 11, v232
	s_nop 0
	v_cndmask_b32_e32 v87, v224, v87, vcc
	v_cmp_le_i32_e32 vcc, v160, v229
	v_add_u32_e32 v160, -16, v232
	s_nop 0
	v_cndmask_b32_e32 v103, v224, v103, vcc
	v_cmp_le_i32_e32 vcc, v160, v229
	v_add_u32_e32 v160, 16, v232
	s_nop 0
	v_cndmask_b32_e32 v88, v224, v88, vcc
	v_cmp_le_i32_e32 vcc, v160, v229
	v_add_u32_e32 v160, -15, v232
	s_nop 0
	v_cndmask_b32_e32 v104, v224, v104, vcc
	v_cmp_le_i32_e32 vcc, v160, v229
	v_add_u32_e32 v160, 17, v232
	s_nop 0
	v_cndmask_b32_e32 v89, v224, v89, vcc
	v_cmp_le_i32_e32 vcc, v160, v229
	v_add_u32_e32 v160, -14, v232
	s_nop 0
	v_cndmask_b32_e32 v105, v224, v105, vcc
	v_cmp_le_i32_e32 vcc, v160, v229
	v_add_u32_e32 v160, 18, v232
	s_nop 0
	v_cndmask_b32_e32 v90, v224, v90, vcc
	v_cmp_le_i32_e32 vcc, v160, v229
	v_add_u32_e32 v160, -13, v232
	s_nop 0
	v_cndmask_b32_e32 v106, v224, v106, vcc
	v_cmp_le_i32_e32 vcc, v160, v229
	v_add_u32_e32 v160, 19, v232
	s_nop 0
	v_cndmask_b32_e32 v91, v224, v91, vcc
	v_cmp_le_i32_e32 vcc, v160, v229
	v_add_u32_e32 v160, -8, v232
	s_nop 0
	v_cndmask_b32_e32 v107, v224, v107, vcc
	v_cmp_le_i32_e32 vcc, v160, v229
	v_add_u32_e32 v160, 24, v232
	s_nop 0
	v_cndmask_b32_e32 v92, v224, v92, vcc
	v_cmp_le_i32_e32 vcc, v160, v229
	v_add_u32_e32 v160, -7, v232
	s_nop 0
	v_cndmask_b32_e32 v108, v224, v108, vcc
	v_cmp_le_i32_e32 vcc, v160, v229
	v_add_u32_e32 v160, 25, v232
	s_nop 0
	v_cndmask_b32_e32 v93, v224, v93, vcc
	v_cmp_le_i32_e32 vcc, v160, v229
	v_add_u32_e32 v160, -6, v232
	s_nop 0
	v_cndmask_b32_e32 v109, v224, v109, vcc
	v_cmp_le_i32_e32 vcc, v160, v229
	v_add_u32_e32 v160, 26, v232
	s_nop 0
	v_cndmask_b32_e32 v94, v224, v94, vcc
	v_cmp_le_i32_e32 vcc, v160, v229
	v_add_u32_e32 v160, -5, v232
	s_nop 0
	v_cndmask_b32_e32 v110, v224, v110, vcc
	v_cmp_le_i32_e32 vcc, v160, v229
	v_add_u32_e32 v160, 27, v232
	s_nop 0
	v_cndmask_b32_e32 v95, v224, v95, vcc
	v_cmp_le_i32_e32 vcc, v160, v229
	s_nop 1
	v_cndmask_b32_e32 v111, v224, v111, vcc
